# v117 stack plus 64-bit accumulator zeroing (64 v_mov_b64 instead of 128 v_mov_b32 before every GEMM unit)
# speedup vs baseline: 1.0085x; 1.0085x over previous
.LBB0_57:
	s_mov_b32 s100, s1
	s_and_b64 s[0:1], s[52:53], exec
	s_cselect_b32 s20, s45, s57
	s_cselect_b32 s21, s44, s56
	s_cselect_b32 s51, s47, s59
	s_cselect_b32 s55, s46, s58
	s_add_u32 s56, s56, 0x40080
	s_addc_u32 s57, s57, 0
	s_add_u32 s62, s58, 0x100
	v_mov_b64_e32 v[0:1], 0
	s_addc_u32 s63, s59, 0
	s_mov_b32 s64, -2
	v_mov_b64_e32 v[2:3], 0
	v_mov_b64_e32 v[8:9], 0
	v_mov_b64_e32 v[10:11], 0
	v_mov_b64_e32 v[16:17], 0
	v_mov_b64_e32 v[18:19], 0
	v_mov_b64_e32 v[24:25], 0
	v_mov_b64_e32 v[26:27], 0
	v_mov_b64_e32 v[32:33], 0
	v_mov_b64_e32 v[34:35], 0
	v_mov_b64_e32 v[40:41], 0
	v_mov_b64_e32 v[42:43], 0
	v_mov_b64_e32 v[48:49], 0
	v_mov_b64_e32 v[50:51], 0
	v_mov_b64_e32 v[56:57], 0
	v_mov_b64_e32 v[58:59], 0
	v_mov_b64_e32 v[4:5], 0
	v_mov_b64_e32 v[6:7], 0
	v_mov_b64_e32 v[12:13], 0
	v_mov_b64_e32 v[14:15], 0
	v_mov_b64_e32 v[20:21], 0
	v_mov_b64_e32 v[22:23], 0
	v_mov_b64_e32 v[28:29], 0
	v_mov_b64_e32 v[30:31], 0
	v_mov_b64_e32 v[36:37], 0
	v_mov_b64_e32 v[38:39], 0
	v_mov_b64_e32 v[44:45], 0
	v_mov_b64_e32 v[46:47], 0
	v_mov_b64_e32 v[52:53], 0
	v_mov_b64_e32 v[54:55], 0
	v_mov_b64_e32 v[60:61], 0
	v_mov_b64_e32 v[62:63], 0
	v_mov_b64_e32 v[64:65], 0
	v_mov_b64_e32 v[66:67], 0
	v_mov_b64_e32 v[72:73], 0
	v_mov_b64_e32 v[74:75], 0
	v_mov_b64_e32 v[80:81], 0
	v_mov_b64_e32 v[82:83], 0
	v_mov_b64_e32 v[88:89], 0
	v_mov_b64_e32 v[90:91], 0
	v_mov_b64_e32 v[96:97], 0
	v_mov_b64_e32 v[98:99], 0
	v_mov_b64_e32 v[104:105], 0
	v_mov_b64_e32 v[106:107], 0
	v_mov_b64_e32 v[112:113], 0
	v_mov_b64_e32 v[114:115], 0
	v_mov_b64_e32 v[120:121], 0
	v_mov_b64_e32 v[122:123], 0
	v_mov_b64_e32 v[68:69], 0
	v_mov_b64_e32 v[70:71], 0
	v_mov_b64_e32 v[76:77], 0
	v_mov_b64_e32 v[78:79], 0
	v_mov_b64_e32 v[84:85], 0
	v_mov_b64_e32 v[86:87], 0
	v_mov_b64_e32 v[92:93], 0
	v_mov_b64_e32 v[94:95], 0
	v_mov_b64_e32 v[100:101], 0
	v_mov_b64_e32 v[102:103], 0
	v_mov_b64_e32 v[108:109], 0
	v_mov_b64_e32 v[110:111], 0
	v_mov_b64_e32 v[116:117], 0
	v_mov_b64_e32 v[118:119], 0
	v_mov_b64_e32 v[124:125], 0
	v_mov_b64_e32 v[126:127], 0

.LBB0_115:
	s_and_b64 s[20:21], s[54:55], exec
	s_cselect_b32 s20, s45, s57
	s_cselect_b32 s21, s44, s56
	s_cselect_b32 s62, s47, s59
	s_cselect_b32 s63, s46, s58
	s_add_u32 s56, s56, 0x40080
	s_addc_u32 s57, s57, 0
	s_add_u32 s64, s58, 0x100
	v_mov_b64_e32 v[0:1], 0
	s_addc_u32 s65, s59, 0
	s_mov_b32 s70, -2
	v_mov_b64_e32 v[2:3], 0
	v_mov_b64_e32 v[4:5], 0
	v_mov_b64_e32 v[6:7], 0
	v_mov_b64_e32 v[8:9], 0
	v_mov_b64_e32 v[10:11], 0
	v_mov_b64_e32 v[12:13], 0
	v_mov_b64_e32 v[14:15], 0
	v_mov_b64_e32 v[16:17], 0
	v_mov_b64_e32 v[18:19], 0
	v_mov_b64_e32 v[20:21], 0
	v_mov_b64_e32 v[22:23], 0
	v_mov_b64_e32 v[24:25], 0
	v_mov_b64_e32 v[26:27], 0
	v_mov_b64_e32 v[28:29], 0
	v_mov_b64_e32 v[30:31], 0
	v_mov_b64_e32 v[64:65], 0
	v_mov_b64_e32 v[66:67], 0
	v_mov_b64_e32 v[68:69], 0
	v_mov_b64_e32 v[70:71], 0
	v_mov_b64_e32 v[72:73], 0
	v_mov_b64_e32 v[74:75], 0
	v_mov_b64_e32 v[76:77], 0
	v_mov_b64_e32 v[78:79], 0
	v_mov_b64_e32 v[80:81], 0
	v_mov_b64_e32 v[82:83], 0
	v_mov_b64_e32 v[84:85], 0
	v_mov_b64_e32 v[86:87], 0
	v_mov_b64_e32 v[88:89], 0
	v_mov_b64_e32 v[90:91], 0
	v_mov_b64_e32 v[92:93], 0
	v_mov_b64_e32 v[94:95], 0
	v_mov_b64_e32 v[32:33], 0
	v_mov_b64_e32 v[34:35], 0
	v_mov_b64_e32 v[36:37], 0
	v_mov_b64_e32 v[38:39], 0
	v_mov_b64_e32 v[40:41], 0
	v_mov_b64_e32 v[42:43], 0
	v_mov_b64_e32 v[44:45], 0
	v_mov_b64_e32 v[46:47], 0
	v_mov_b64_e32 v[48:49], 0
	v_mov_b64_e32 v[50:51], 0
	v_mov_b64_e32 v[52:53], 0
	v_mov_b64_e32 v[54:55], 0
	v_mov_b64_e32 v[56:57], 0
	v_mov_b64_e32 v[58:59], 0
	v_mov_b64_e32 v[60:61], 0
	v_mov_b64_e32 v[62:63], 0
	v_mov_b64_e32 v[96:97], 0
	v_mov_b64_e32 v[98:99], 0
	v_mov_b64_e32 v[100:101], 0
	v_mov_b64_e32 v[102:103], 0
	v_mov_b64_e32 v[104:105], 0
	v_mov_b64_e32 v[106:107], 0
	v_mov_b64_e32 v[108:109], 0
	v_mov_b64_e32 v[110:111], 0
	v_mov_b64_e32 v[112:113], 0
	v_mov_b64_e32 v[114:115], 0
	v_mov_b64_e32 v[116:117], 0
	v_mov_b64_e32 v[118:119], 0
	v_mov_b64_e32 v[120:121], 0
	v_mov_b64_e32 v[122:123], 0
	v_mov_b64_e32 v[124:125], 0
	v_mov_b64_e32 v[126:127], 0

.LBB0_153:
	s_add_u32 s54, s54, 0x80080
	s_addc_u32 s55, s55, 0
	s_add_u32 s20, s56, 0x100
	v_mov_b64_e32 v[0:1], 0
	s_addc_u32 s21, s57, 0
	s_mov_b32 s30, -2
	v_mov_b64_e32 v[2:3], 0
	v_mov_b64_e32 v[4:5], 0
	v_mov_b64_e32 v[6:7], 0
	v_mov_b64_e32 v[16:17], 0
	v_mov_b64_e32 v[18:19], 0
	v_mov_b64_e32 v[20:21], 0
	v_mov_b64_e32 v[22:23], 0
	v_mov_b64_e32 v[32:33], 0
	v_mov_b64_e32 v[34:35], 0
	v_mov_b64_e32 v[36:37], 0
	v_mov_b64_e32 v[38:39], 0
	v_mov_b64_e32 v[48:49], 0
	v_mov_b64_e32 v[50:51], 0
	v_mov_b64_e32 v[52:53], 0
	v_mov_b64_e32 v[54:55], 0
	v_mov_b64_e32 v[8:9], 0
	v_mov_b64_e32 v[10:11], 0
	v_mov_b64_e32 v[12:13], 0
	v_mov_b64_e32 v[14:15], 0
	v_mov_b64_e32 v[24:25], 0
	v_mov_b64_e32 v[26:27], 0
	v_mov_b64_e32 v[28:29], 0
	v_mov_b64_e32 v[30:31], 0
	v_mov_b64_e32 v[40:41], 0
	v_mov_b64_e32 v[42:43], 0
	v_mov_b64_e32 v[44:45], 0
	v_mov_b64_e32 v[46:47], 0
	v_mov_b64_e32 v[56:57], 0
	v_mov_b64_e32 v[58:59], 0
	v_mov_b64_e32 v[60:61], 0
	v_mov_b64_e32 v[62:63], 0
	v_mov_b64_e32 v[64:65], 0
	v_mov_b64_e32 v[66:67], 0
	v_mov_b64_e32 v[68:69], 0
	v_mov_b64_e32 v[70:71], 0
	v_mov_b64_e32 v[80:81], 0
	v_mov_b64_e32 v[82:83], 0
	v_mov_b64_e32 v[84:85], 0
	v_mov_b64_e32 v[86:87], 0
	v_mov_b64_e32 v[96:97], 0
	v_mov_b64_e32 v[98:99], 0
	v_mov_b64_e32 v[100:101], 0
	v_mov_b64_e32 v[102:103], 0
	v_mov_b64_e32 v[112:113], 0
	v_mov_b64_e32 v[114:115], 0
	v_mov_b64_e32 v[116:117], 0
	v_mov_b64_e32 v[118:119], 0
	v_mov_b64_e32 v[72:73], 0
	v_mov_b64_e32 v[74:75], 0
	v_mov_b64_e32 v[76:77], 0
	v_mov_b64_e32 v[78:79], 0
	v_mov_b64_e32 v[88:89], 0
	v_mov_b64_e32 v[90:91], 0
	v_mov_b64_e32 v[92:93], 0
	v_mov_b64_e32 v[94:95], 0
	v_mov_b64_e32 v[104:105], 0
	v_mov_b64_e32 v[106:107], 0
	v_mov_b64_e32 v[108:109], 0
	v_mov_b64_e32 v[110:111], 0
	v_mov_b64_e32 v[122:123], 0
	v_mov_b64_e32 v[124:125], 0
	v_mov_b64_e32 v[126:127], 0
	v_mov_b64_e32 v[128:129], 0

.LBB0_644:
	s_mov_b32 s100, s30
	s_and_b64 s[0:1], s[58:59], exec
	s_cselect_b32 s0, s49, s43
	s_cselect_b32 s1, s48, s42
	s_cselect_b32 s20, s51, s45
	s_cselect_b32 s21, s50, s44
	s_add_u32 s42, s42, 0x40080
	s_addc_u32 s43, s43, 0
	s_add_u32 s22, s44, 0x100
	v_mov_b64_e32 v[0:1], 0
	s_addc_u32 s30, s45, 0
	s_mov_b32 s64, -2
	v_mov_b64_e32 v[2:3], 0
	v_mov_b64_e32 v[4:5], 0
	v_mov_b64_e32 v[6:7], 0
	v_mov_b64_e32 v[8:9], 0
	v_mov_b64_e32 v[10:11], 0
	v_mov_b64_e32 v[12:13], 0
	v_mov_b64_e32 v[14:15], 0
	v_mov_b64_e32 v[24:25], 0
	v_mov_b64_e32 v[26:27], 0
	v_mov_b64_e32 v[28:29], 0
	v_mov_b64_e32 v[30:31], 0
	v_mov_b64_e32 v[40:41], 0
	v_mov_b64_e32 v[42:43], 0
	v_mov_b64_e32 v[44:45], 0
	v_mov_b64_e32 v[46:47], 0
	v_mov_b64_e32 v[16:17], 0
	v_mov_b64_e32 v[18:19], 0
	v_mov_b64_e32 v[20:21], 0
	v_mov_b64_e32 v[22:23], 0
	v_mov_b64_e32 v[32:33], 0
	v_mov_b64_e32 v[34:35], 0
	v_mov_b64_e32 v[36:37], 0
	v_mov_b64_e32 v[38:39], 0
	v_mov_b64_e32 v[48:49], 0
	v_mov_b64_e32 v[50:51], 0
	v_mov_b64_e32 v[52:53], 0
	v_mov_b64_e32 v[54:55], 0
	v_mov_b64_e32 v[56:57], 0
	v_mov_b64_e32 v[58:59], 0
	v_mov_b64_e32 v[60:61], 0
	v_mov_b64_e32 v[62:63], 0
	v_mov_b64_e32 v[64:65], 0
	v_mov_b64_e32 v[66:67], 0
	v_mov_b64_e32 v[68:69], 0
	v_mov_b64_e32 v[70:71], 0
	v_mov_b64_e32 v[72:73], 0
	v_mov_b64_e32 v[74:75], 0
	v_mov_b64_e32 v[76:77], 0
	v_mov_b64_e32 v[78:79], 0
	v_mov_b64_e32 v[88:89], 0
	v_mov_b64_e32 v[90:91], 0
	v_mov_b64_e32 v[92:93], 0
	v_mov_b64_e32 v[94:95], 0
	v_mov_b64_e32 v[104:105], 0
	v_mov_b64_e32 v[106:107], 0
	v_mov_b64_e32 v[108:109], 0
	v_mov_b64_e32 v[110:111], 0
	v_mov_b64_e32 v[80:81], 0
	v_mov_b64_e32 v[82:83], 0
	v_mov_b64_e32 v[84:85], 0
	v_mov_b64_e32 v[86:87], 0
	v_mov_b64_e32 v[96:97], 0
	v_mov_b64_e32 v[98:99], 0
	v_mov_b64_e32 v[100:101], 0
	v_mov_b64_e32 v[102:103], 0
	v_mov_b64_e32 v[112:113], 0
	v_mov_b64_e32 v[114:115], 0
	v_mov_b64_e32 v[116:117], 0
	v_mov_b64_e32 v[118:119], 0
	v_mov_b64_e32 v[120:121], 0
	v_mov_b64_e32 v[122:123], 0
	v_mov_b64_e32 v[124:125], 0
	v_mov_b64_e32 v[126:127], 0

.LBB0_1250:
	s_and_b64 s[20:21], s[52:53], exec
	s_cselect_b32 s20, s45, s55
	s_cselect_b32 s21, s44, s54
	s_cselect_b32 s70, s47, s57
	s_cselect_b32 vcc_lo, s46, s56
	s_add_u32 vcc_hi, s56, 0x100
	v_mov_b64_e32 v[0:1], 0
	s_addc_u32 s48, s57, 0
	s_mov_b32 s49, -2
	v_mov_b64_e32 v[2:3], 0
	v_mov_b64_e32 v[4:5], 0
	v_mov_b64_e32 v[6:7], 0
	v_mov_b64_e32 v[8:9], 0
	v_mov_b64_e32 v[10:11], 0
	v_mov_b64_e32 v[12:13], 0
	v_mov_b64_e32 v[14:15], 0
	v_mov_b64_e32 v[16:17], 0
	v_mov_b64_e32 v[18:19], 0
	v_mov_b64_e32 v[20:21], 0
	v_mov_b64_e32 v[22:23], 0
	v_mov_b64_e32 v[24:25], 0
	v_mov_b64_e32 v[26:27], 0
	v_mov_b64_e32 v[28:29], 0
	v_mov_b64_e32 v[30:31], 0
	v_mov_b64_e32 v[64:65], 0
	v_mov_b64_e32 v[66:67], 0
	v_mov_b64_e32 v[68:69], 0
	v_mov_b64_e32 v[70:71], 0
	v_mov_b64_e32 v[72:73], 0
	v_mov_b64_e32 v[74:75], 0
	v_mov_b64_e32 v[76:77], 0
	v_mov_b64_e32 v[78:79], 0
	v_mov_b64_e32 v[80:81], 0
	v_mov_b64_e32 v[82:83], 0
	v_mov_b64_e32 v[84:85], 0
	v_mov_b64_e32 v[86:87], 0
	v_mov_b64_e32 v[88:89], 0
	v_mov_b64_e32 v[90:91], 0
	v_mov_b64_e32 v[92:93], 0
	v_mov_b64_e32 v[94:95], 0
	v_mov_b64_e32 v[32:33], 0
	v_mov_b64_e32 v[34:35], 0
	v_mov_b64_e32 v[36:37], 0
	v_mov_b64_e32 v[38:39], 0
	v_mov_b64_e32 v[40:41], 0
	v_mov_b64_e32 v[42:43], 0
	v_mov_b64_e32 v[44:45], 0
	v_mov_b64_e32 v[46:47], 0
	v_mov_b64_e32 v[48:49], 0
	v_mov_b64_e32 v[50:51], 0
	v_mov_b64_e32 v[52:53], 0
	v_mov_b64_e32 v[54:55], 0
	v_mov_b64_e32 v[56:57], 0
	v_mov_b64_e32 v[58:59], 0
	v_mov_b64_e32 v[60:61], 0
	v_mov_b64_e32 v[62:63], 0
	v_mov_b64_e32 v[96:97], 0
	v_mov_b64_e32 v[98:99], 0
	v_mov_b64_e32 v[100:101], 0
	v_mov_b64_e32 v[102:103], 0
	v_mov_b64_e32 v[104:105], 0
	v_mov_b64_e32 v[106:107], 0
	v_mov_b64_e32 v[108:109], 0
	v_mov_b64_e32 v[110:111], 0
	v_mov_b64_e32 v[112:113], 0
	v_mov_b64_e32 v[114:115], 0
	v_mov_b64_e32 v[116:117], 0
	v_mov_b64_e32 v[118:119], 0
	v_mov_b64_e32 v[120:121], 0
	v_mov_b64_e32 v[122:123], 0
	v_mov_b64_e32 v[124:125], 0
	v_mov_b64_e32 v[126:127], 0
